# MoBA prologue: block-mean loop issues its 8 loads before one wait, gate query quads requested at item top; dilated-combine item: output/gate loads issued with the LSE loads (one round trip)
# speedup vs baseline: 1.0208x; 1.0035x over previous
.LBB0_331:
	v_mov_b32_e32 v8, v254
	v_add_u32_e32 v254, v254, v255
	s_mov_b64 s[2:3], -1
	v_cmp_gt_i32_e32 vcc, 64, v8
	s_and_saveexec_b64 s[82:83], vcc
	s_cbranch_execz .LBB0_330
	v_ashrrev_i32_e32 v33, 2, v8
	v_sub_u32_e32 v7, 15, v33
	v_mov_b32_e32 v3, v197
	v_lshlrev_b32_e32 v0, 5, v8
	v_readlane_b32 s2, v249, 37
	v_lshlrev_b32_e32 v9, 6, v7
	s_nop 0
	v_and_or_b32 v32, v0, 64, s2
	v_cmp_lt_i32_e32 vcc, v3, v9
	s_barrier
	v_and_b32_e32 v216, 1, v8
	v_readlane_b32 s2, v249, 36
	v_lshlrev_b32_e32 v217, 7, v216
	v_ashrrev_i32_e32 v218, 1, v3
	v_lshl_add_u32 v219, v7, 8, s2
	v_or_b32_e32 v219, v219, v217
	v_add_u32_e32 v218, v218, v219
	v_mov_b64_e32 v[220:221], s[4:5]
	v_mad_i64_i32 v[220:221], s[2:3], v218, s93, v[220:221]
	v_lshlrev_b32_e32 v222, 1, v32
	v_mov_b32_e32 v223, v2
	v_lshl_add_u64 v[220:221], v[220:221], 0, v[222:223]
	global_load_dwordx4 v[154:157], v[220:221], off
	global_load_dwordx4 v[158:161], v[220:221], off offset:16
	global_load_dwordx4 v[162:165], v[220:221], off offset:32
	global_load_dwordx4 v[166:169], v[220:221], off offset:48
	global_load_dwordx4 v[170:173], v[220:221], off offset:64
	global_load_dwordx4 v[174:177], v[220:221], off offset:80
	global_load_dwordx4 v[178:181], v[220:221], off offset:96
	global_load_dwordx4 v[182:185], v[220:221], off offset:112
	s_and_saveexec_b64 s[2:3], vcc
	s_cbranch_execz .LBB0_344
	v_readlane_b32 s8, v249, 38
	v_lshlrev_b32_e32 v0, 2, v32
	v_mov_b32_e32 v1, v2
	v_readlane_b32 s9, v249, 39
	v_and_b32_e32 v4, 63, v3
	v_lshlrev_b32_e32 v4, 2, v4
	v_lshl_add_u64 v[0:1], s[8:9], 0, v[0:1]
	v_mov_b32_e32 v5, v2
	v_lshl_add_u64 v[0:1], v[0:1], 0, v[4:5]
	v_add_u32_e32 v5, 0x100, v3
	v_max_i32_e32 v4, v9, v5
	v_xad_u32 v12, v3, -1, v4
	s_movk_i32 s8, 0xff
	v_cmp_lt_u32_e32 vcc, s8, v12
	s_mov_b64 s[10:11], -1
	v_mov_b32_e32 v4, v3
	s_and_saveexec_b64 s[8:9], vcc
	s_cbranch_execz .LBB0_341
	v_lshrrev_b32_e32 v4, 8, v12
	v_add_u32_e32 v12, 1, v4
	v_and_b32_e32 v13, 0x1fffffe, v12
	v_mov_b32_e32 v4, v3
	v_lshl_add_u32 v15, v3, 2, v210
	s_mov_b64 s[10:11], 0
	v_mov_b32_e32 v16, v13
	v_readlane_b32 s15, v248, 5
.LBB0_339:
	v_ashrrev_i32_e32 v19, 4, v4
	v_ashrrev_i32_e32 v17, 4, v5
	v_and_b32_e32 v19, -4, v19
	v_and_b32_e32 v17, -4, v17
	v_add_u32_e32 v22, s23, v19
	v_add_u32_e32 v20, s15, v17
	v_ashrrev_i32_e32 v23, 31, v22
	v_ashrrev_i32_e32 v21, 31, v20
	v_lshlrev_b64 v[22:23], 10, v[22:23]
	v_lshlrev_b64 v[20:21], 10, v[20:21]
	v_lshl_add_u64 v[22:23], v[0:1], 0, v[22:23]
	v_lshl_add_u64 v[20:21], v[0:1], 0, v[20:21]
	global_load_dword v24, v[22:23], off
	global_load_dword v25, v[20:21], off
	global_load_dword v26, v[22:23], off offset:1024
	global_load_dword v27, v[20:21], off offset:1024
	s_mov_b32 s14, 0x3b800000
	v_add_u32_e32 v16, -2, v16
	v_cmp_eq_u32_e32 vcc, 0, v16
	v_add_u32_e32 v5, 0x200, v5
	v_add_u32_e32 v4, 0x200, v4
	s_or_b64 s[10:11], vcc, s[10:11]
	global_load_dword v216, v[22:23], off offset:2048
	global_load_dword v217, v[20:21], off offset:2048
	global_load_dword v218, v[22:23], off offset:3072
	global_load_dword v219, v[20:21], off offset:3072
	s_waitcnt vmcnt(0)
	v_pk_add_f32 v[24:25], v[24:25], v[26:27]
	v_pk_add_f32 v[20:21], v[216:217], v[218:219]
	s_nop 0
	v_pk_add_f32 v[20:21], v[24:25], v[20:21]
	s_nop 0
	v_pk_mul_f32 v[20:21], v[20:21], s[14:15] op_sel_hi:[1,0]
	ds_write2st64_b32 v15, v20, v21 offset1:4
	v_add_u32_e32 v15, 0x800, v15
	s_andn2_b64 exec, exec, s[10:11]
	s_cbranch_execnz .LBB0_339
	s_or_b64 exec, exec, s[10:11]
	v_cmp_ne_u32_e32 vcc, v12, v13
	v_lshl_add_u32 v4, v13, 8, v3
	s_orn2_b64 s[10:11], vcc, exec

.LBB0_589:
	v_mov_b32_e32 v3, v197
	s_ashr_i32 s3, s2, 31
	v_ashrrev_i32_e32 v0, 5, v3
	v_ashrrev_i32_e32 v1, 31, v0
	v_lshl_add_u64 v[0:1], s[2:3], 3, v[0:1]
	v_and_b32_e32 v7, 31, v3
	v_lshrrev_b32_e32 v3, 1, v3
	v_lshl_add_u64 v[4:5], v[0:1], 4, s[10:11]
	v_and_b32_e32 v8, 12, v3
	v_mov_b32_e32 v9, v2
	v_lshl_add_u64 v[4:5], v[4:5], 0, v[8:9]
	v_lshl_add_u64 v[12:13], v[0:1], 0, s[14:15]
	global_load_dword v3, v[4:5], off
	v_lshl_add_u64 v[4:5], v[12:13], 4, s[10:11]
	v_lshl_add_u64 v[4:5], v[4:5], 0, v[8:9]
	v_lshl_add_u64 v[16:17], v[0:1], 0, s[38:39]
	global_load_dword v15, v[4:5], off
	v_lshl_add_u64 v[4:5], v[16:17], 4, s[10:11]
	v_lshl_add_u64 v[4:5], v[4:5], 0, v[8:9]
	global_load_dword v4, v[4:5], off
	v_lshlrev_b64 v[12:13], 9, v[12:13]
	v_lshl_add_u64 v[12:13], s[34:35], 0, v[12:13]
	s_mov_b32 s3, 0x35a1000
	s_add_i32 s2, s2, s26
	s_cmpk_gt_i32 s2, 0x7ff
	v_lshlrev_b64 v[216:217], 9, v[0:1]
	v_lshl_add_u64 v[216:217], s[34:35], 0, v[216:217]
	v_lshlrev_b32_e32 v218, 4, v7
	v_mov_b32_e32 v219, v2
	v_lshl_add_u64 v[216:217], v[216:217], 0, v[218:219]
	global_load_dwordx4 v[24:27], v[216:217], off nt
	v_lshl_add_u64 v[220:221], v[12:13], 0, v[218:219]
	global_load_dwordx4 v[28:31], v[220:221], off nt
	v_lshlrev_b64 v[220:221], 9, v[16:17]
	v_lshl_add_u64 v[220:221], s[34:35], 0, v[220:221]
	v_lshl_add_u64 v[220:221], v[220:221], 0, v[218:219]
	global_load_dwordx4 v[32:35], v[220:221], off nt
	v_mov_b64_e32 v[220:221], s[24:25]
	v_mad_u64_u32 v[220:221], s[8:9], v0, s93, v[220:221]
	v_mad_i32_i24 v221, v1, s93, v221
	v_lshl_add_u64 v[220:221], v[220:221], 0, v[218:219]
	v_add_co_u32_e32 v220, vcc, s3, v220
	s_nop 1
	v_addc_co_u32_e32 v221, vcc, 0, v221, vcc
	global_load_dwordx4 v[20:23], v[220:221], off offset:512
	s_waitcnt vmcnt(4)
	v_max3_f32 v5, v3, v15, v4
	v_sub_f32_e32 v3, v3, v5
	v_mul_f32_e32 v3, 0x3fb8aa3b, v3
	v_exp_f32_e32 v37, v3
	v_sub_f32_e32 v3, v15, v5
	v_mul_f32_e32 v3, 0x3fb8aa3b, v3
	v_exp_f32_e32 v36, v3
	v_sub_f32_e32 v3, v4, v5
	v_mul_f32_e32 v3, 0x3fb8aa3b, v3
	v_exp_f32_e32 v3, v3
	v_add_f32_e32 v4, v37, v36
	v_add_f32_e32 v4, v3, v4
	v_div_scale_f32 v5, s[8:9], v4, v4, 1.0
	v_rcp_f32_e32 v8, v5
	s_nop 0
	v_fma_f32 v9, -v5, v8, 1.0
	v_fmac_f32_e32 v8, v9, v8
	v_div_scale_f32 v9, vcc, 1.0, v4, 1.0
	v_mul_f32_e32 v15, v9, v8
	v_fma_f32 v19, -v5, v15, v9
	v_fmac_f32_e32 v15, v19, v8
	v_fma_f32 v5, -v5, v15, v9
	v_div_fmas_f32 v5, v5, v8, v15
	v_div_fixup_f32 v38, v5, v4, 1.0
	v_lshlrev_b64 v[4:5], 9, v[0:1]
	v_lshlrev_b32_e32 v4, 4, v7
	v_mov_b32_e32 v5, v2
	v_lshl_add_u64 v[12:13], v[12:13], 0, v[4:5]
	v_lshlrev_b64 v[12:13], 9, v[16:17]
	v_lshl_add_u64 v[12:13], s[34:35], 0, v[12:13]
	v_lshl_add_u64 v[12:13], v[12:13], 0, v[4:5]
	v_mov_b64_e32 v[12:13], s[24:25]
	v_mad_u64_u32 v[12:13], s[8:9], v0, s93, v[12:13]
	v_mad_i32_i24 v13, v1, s93, v13
	v_lshl_add_u64 v[16:17], v[12:13], 0, v[4:5]
	v_add_co_u32_e32 v16, vcc, s3, v16
	v_mul_f32_e32 v8, v3, v38
	s_nop 0
	v_addc_co_u32_e32 v17, vcc, 0, v17, vcc
	v_pk_mul_f32 v[16:17], v[36:37], v[38:39] op_sel_hi:[1,0]
	s_waitcnt vmcnt(3)
	v_and_b32_e32 v37, 0xffff0000, v24
	v_lshlrev_b32_e32 v38, 16, v24
	s_waitcnt vmcnt(2)
	v_and_b32_e32 v39, 0xffff0000, v28
	v_lshlrev_b32_e32 v36, 16, v28
	v_pk_mul_f32 v[38:39], v[16:17], v[38:39] op_sel:[1,0] op_sel_hi:[0,1]
	s_waitcnt vmcnt(1)
	v_lshlrev_b32_e32 v40, 16, v32
	v_and_b32_e32 v41, 0xffff0000, v32
	v_pk_fma_f32 v[36:37], v[16:17], v[36:37], v[38:39]
	v_lshlrev_b32_e32 v28, 16, v33
	s_waitcnt vmcnt(0)
	v_lshlrev_b32_e32 v3, 16, v20
	v_and_b32_e32 v7, 0xffff0000, v20
	v_mul_f32_e32 v9, 0xbfb8aa3b, v3
	v_exp_f32_e32 v42, v9
	v_mul_f32_e32 v9, 0xbfb8aa3b, v7
	v_exp_f32_e32 v43, v9
	s_nop 0
	v_pk_add_f32 v[42:43], v[42:43], 1.0 op_sel_hi:[1,0]
	s_nop 0
	v_div_scale_f32 v9, s[8:9], v43, v43, v7
	v_rcp_f32_e32 v15, v9
	s_nop 0
	v_fma_f32 v19, -v9, v15, 1.0
	v_fmac_f32_e32 v15, v19, v15
	v_div_scale_f32 v19, vcc, v7, v43, v7
	v_mul_f32_e32 v20, v19, v15
	v_fma_f32 v24, -v9, v20, v19
	v_fmac_f32_e32 v20, v24, v15
	v_fma_f32 v9, -v9, v20, v19
	v_div_fmas_f32 v9, v9, v15, v20
	v_div_fixup_f32 v43, v9, v43, v7
	v_div_scale_f32 v7, s[8:9], v42, v42, v3
	v_rcp_f32_e32 v9, v7
	v_lshlrev_b32_e32 v24, 16, v25
	v_fma_f32 v15, -v7, v9, 1.0
	v_fmac_f32_e32 v9, v15, v9
	v_div_scale_f32 v15, vcc, v3, v42, v3
	v_mul_f32_e32 v19, v15, v9
	v_fma_f32 v20, -v7, v19, v15
	v_fmac_f32_e32 v19, v20, v9
	v_fma_f32 v7, -v7, v19, v15
	v_div_fmas_f32 v7, v7, v9, v19
	v_div_fixup_f32 v42, v7, v42, v3
	v_lshlrev_b32_e32 v3, 16, v21
	v_pk_fma_f32 v[36:37], v[8:9], v[40:41], v[36:37] op_sel_hi:[0,1,1]
	v_and_b32_e32 v7, 0xffff0000, v21
	v_mul_f32_e32 v9, 0xbfb8aa3b, v3
	v_pk_mul_f32 v[36:37], v[42:43], v[36:37]
	v_exp_f32_e32 v32, v9
	v_mul_f32_e32 v9, 0xbfb8aa3b, v7
	v_cvt_pk_bf16_f32 v20, v36, v37
	v_lshlrev_b32_e32 v36, 16, v29
	v_and_b32_e32 v37, 0xffff0000, v25
	v_and_b32_e32 v25, 0xffff0000, v29
	v_and_b32_e32 v29, 0xffff0000, v33
	v_exp_f32_e32 v33, v9
	v_pk_mul_f32 v[24:25], v[16:17], v[24:25] op_sel:[1,0] op_sel_hi:[0,1]
	v_pk_fma_f32 v[24:25], v[16:17], v[36:37], v[24:25]
	v_pk_add_f32 v[32:33], v[32:33], 1.0 op_sel_hi:[1,0]
	s_nop 0
	v_div_scale_f32 v9, s[8:9], v33, v33, v7
	v_rcp_f32_e32 v15, v9
	s_nop 0
	v_fma_f32 v19, -v9, v15, 1.0
	v_fmac_f32_e32 v15, v19, v15
	v_div_scale_f32 v19, vcc, v7, v33, v7
	v_mul_f32_e32 v21, v19, v15
	v_fma_f32 v38, -v9, v21, v19
	v_fmac_f32_e32 v21, v38, v15
	v_fma_f32 v9, -v9, v21, v19
	v_div_fmas_f32 v9, v9, v15, v21
	v_div_fixup_f32 v33, v9, v33, v7
	v_div_scale_f32 v7, s[8:9], v32, v32, v3
	v_rcp_f32_e32 v9, v7
	s_nop 0
	v_fma_f32 v15, -v7, v9, 1.0
	v_fmac_f32_e32 v9, v15, v9
	v_div_scale_f32 v15, vcc, v3, v32, v3
	v_mul_f32_e32 v19, v15, v9
	v_fma_f32 v21, -v7, v19, v15
	v_fmac_f32_e32 v19, v21, v9
	v_fma_f32 v7, -v7, v19, v15
	v_div_fmas_f32 v7, v7, v9, v19
	v_div_fixup_f32 v32, v7, v32, v3
	v_lshlrev_b32_e32 v3, 16, v22
	v_pk_fma_f32 v[24:25], v[8:9], v[28:29], v[24:25] op_sel_hi:[0,1,1]
	v_and_b32_e32 v7, 0xffff0000, v22
	v_mul_f32_e32 v9, 0xbfb8aa3b, v3
	v_exp_f32_e32 v36, v9
	v_mul_f32_e32 v9, 0xbfb8aa3b, v7
	v_exp_f32_e32 v37, v9
	v_pk_mul_f32 v[24:25], v[32:33], v[24:25]
	v_lshlrev_b32_e32 v28, 16, v26
	v_cvt_pk_bf16_f32 v21, v24, v25
	v_pk_add_f32 v[36:37], v[36:37], 1.0 op_sel_hi:[1,0]
	v_and_b32_e32 v25, 0xffff0000, v26
	v_div_scale_f32 v9, s[8:9], v37, v37, v7
	v_rcp_f32_e32 v15, v9
	v_and_b32_e32 v29, 0xffff0000, v30
	v_lshlrev_b32_e32 v24, 16, v30
	v_pk_mul_f32 v[28:29], v[16:17], v[28:29] op_sel:[1,0] op_sel_hi:[0,1]
	v_fma_f32 v19, -v9, v15, 1.0
	v_fmac_f32_e32 v15, v19, v15
	v_div_scale_f32 v19, vcc, v7, v37, v7
	v_mul_f32_e32 v22, v19, v15
	v_fma_f32 v26, -v9, v22, v19
	v_fmac_f32_e32 v22, v26, v15
	v_fma_f32 v9, -v9, v22, v19
	v_div_fmas_f32 v9, v9, v15, v22
	v_div_fixup_f32 v37, v9, v37, v7
	v_div_scale_f32 v7, s[8:9], v36, v36, v3
	v_rcp_f32_e32 v9, v7
	v_lshlrev_b32_e32 v32, 16, v34
	v_and_b32_e32 v33, 0xffff0000, v34
	v_pk_fma_f32 v[24:25], v[16:17], v[24:25], v[28:29]
	v_fma_f32 v15, -v7, v9, 1.0
	v_fmac_f32_e32 v9, v15, v9
	v_div_scale_f32 v15, vcc, v3, v36, v3
	v_mul_f32_e32 v19, v15, v9
	v_fma_f32 v22, -v7, v19, v15
	v_fmac_f32_e32 v19, v22, v9
	v_fma_f32 v7, -v7, v19, v15
	v_div_fmas_f32 v7, v7, v9, v19
	v_div_fixup_f32 v36, v7, v36, v3
	v_pk_fma_f32 v[24:25], v[8:9], v[32:33], v[24:25] op_sel_hi:[0,1,1]
	v_pk_mul_f32 v[24:25], v[36:37], v[24:25]
	v_lshlrev_b32_e32 v26, 16, v27
	v_cvt_pk_bf16_f32 v22, v24, v25
	v_and_b32_e32 v25, 0xffff0000, v27
	v_and_b32_e32 v27, 0xffff0000, v31
	v_lshlrev_b32_e32 v24, 16, v31
	v_pk_mul_f32 v[26:27], v[16:17], v[26:27] op_sel:[1,0] op_sel_hi:[0,1]
	v_lshlrev_b32_e32 v3, 16, v23
	v_pk_fma_f32 v[16:17], v[16:17], v[24:25], v[26:27]
	v_lshlrev_b32_e32 v24, 16, v35
	v_and_b32_e32 v25, 0xffff0000, v35
	v_and_b32_e32 v7, 0xffff0000, v23
	v_mul_f32_e32 v15, 0xbfb8aa3b, v3
	v_pk_fma_f32 v[8:9], v[8:9], v[24:25], v[16:17] op_sel_hi:[0,1,1]
	v_exp_f32_e32 v16, v15
	v_mul_f32_e32 v15, 0xbfb8aa3b, v7
	v_exp_f32_e32 v17, v15
	s_nop 0
	v_pk_add_f32 v[16:17], v[16:17], 1.0 op_sel_hi:[1,0]
	s_nop 0
	v_div_scale_f32 v15, s[8:9], v17, v17, v7
	v_rcp_f32_e32 v19, v15
	s_nop 0
	v_fma_f32 v23, -v15, v19, 1.0
	v_fmac_f32_e32 v19, v23, v19
	v_div_scale_f32 v23, vcc, v7, v17, v7
	v_mul_f32_e32 v24, v23, v19
	v_fma_f32 v25, -v15, v24, v23
	v_fmac_f32_e32 v24, v25, v19
	v_fma_f32 v15, -v15, v24, v23
	v_div_fmas_f32 v15, v15, v19, v24
	v_div_fixup_f32 v17, v15, v17, v7
	v_div_scale_f32 v7, s[8:9], v16, v16, v3
	v_rcp_f32_e32 v15, v7
	s_nop 0
	v_fma_f32 v19, -v7, v15, 1.0
	v_fmac_f32_e32 v15, v19, v15
	v_div_scale_f32 v19, vcc, v3, v16, v3
	v_mul_f32_e32 v23, v19, v15
	v_fma_f32 v24, -v7, v23, v19
	v_fmac_f32_e32 v23, v24, v15
	v_fma_f32 v7, -v7, v23, v19
	v_div_fmas_f32 v7, v7, v15, v23
	v_div_fixup_f32 v16, v7, v16, v3
	v_pk_mul_f32 v[8:9], v[16:17], v[8:9]
	s_nop 0
	v_cvt_pk_bf16_f32 v23, v8, v9
	v_mad_u64_u32 v[8:9], s[8:9], v0, s12, v[12:13]
	v_mad_i32_i24 v1, v1, s12, v9
	v_sub_u32_e32 v9, v1, v0
	v_lshl_add_u64 v[0:1], v[8:9], 0, v[4:5]
	v_add_co_u32_e32 v0, vcc, 0x15a0000, v0
	s_nop 1
	v_addc_co_u32_e32 v1, vcc, 0, v1, vcc
	global_store_dwordx4 v[0:1], v[20:23], off offset:1024
	s_cbranch_scc0 .LBB0_589
